# grid barrier: L1 invalidate issued before the polls (overlaps the wait) instead of after the release
# speedup vs baseline: 1.0123x; 1.0123x over previous
.LBB0_571:
	s_or_b64 exec, exec, s[2:3]
	v_cvt_f32_u32_e32 v5, v3
	s_waitcnt vmcnt(0)
	v_readfirstlane_b32 s2, v4
	v_sub_u32_e32 v4, 0, v3
	v_rcp_iflag_f32_e32 v5, v5
	v_add_u32_e32 v6, s2, v0
	v_mul_f32_e32 v5, 0x4f7ffffe, v5
	v_cvt_u32_f32_e32 v5, v5
	v_mul_lo_u32 v0, v4, v5
	v_mul_hi_u32 v0, v5, v0
	v_add_u32_e32 v0, v5, v0
	v_mul_hi_u32 v0, v6, v0
	v_mul_lo_u32 v4, v0, v3
	v_sub_u32_e32 v4, v6, v4
	v_add_u32_e32 v5, 1, v0
	v_cmp_ge_u32_e32 vcc, v4, v3
	s_nop 1
	v_cndmask_b32_e32 v0, v0, v5, vcc
	v_sub_u32_e32 v5, v4, v3
	v_cndmask_b32_e32 v4, v4, v5, vcc
	v_add_u32_e32 v5, 1, v0
	v_cmp_ge_u32_e32 vcc, v4, v3
	v_add_u32_e32 v4, 1, v6
	s_nop 0
	v_cndmask_b32_e32 v0, v0, v5, vcc
	v_mul_lo_u32 v5, v3, v0
	v_add_u32_e32 v3, v5, v3
	v_cmp_ne_u32_e32 vcc, v4, v3
	s_and_saveexec_b64 s[2:3], vcc
	s_xor_b64 s[2:3], exec, s[2:3]
	s_cbranch_execz .LBB0_585
	v_readlane_b32 s4, v215, 22
	v_readlane_b32 s5, v215, 23
	s_waitcnt lgkmcnt(0)
	s_nop 3
	buffer_inv sc1
	global_load_dword v2, v1, s[4:5] sc1
	s_waitcnt vmcnt(0)
	v_cmp_eq_u32_e32 vcc, v2, v0
	s_and_saveexec_b64 s[4:5], vcc
	s_cbranch_execz .LBB0_584
	s_mov_b32 s16, 1
	s_mov_b64 s[6:7], 0
	s_branch .LBB0_575

.LBB0_584:
	s_or_b64 exec, exec, s[4:5]
	s_waitcnt vmcnt(0)
	s_waitcnt vmcnt(0)

.LBB0_588:
	s_or_b64 exec, exec, s[4:5]
	buffer_inv sc1
	s_waitcnt vmcnt(0)
	v_readfirstlane_b32 s2, v3
	v_sub_u32_e32 v4, 0, v2
	s_mov_b64 s[4:5], -1
	v_add_u32_e32 v3, s2, v0
	v_cvt_f32_u32_e32 v0, v2
	v_readlane_b32 s2, v215, 26
	v_readlane_b32 s3, v215, 27
	v_rcp_iflag_f32_e32 v0, v0
	s_nop 0
	v_mul_f32_e32 v0, 0x4f7ffffe, v0
	v_cvt_u32_f32_e32 v0, v0
	v_mul_lo_u32 v4, v4, v0
	v_mul_hi_u32 v4, v0, v4
	v_add_u32_e32 v0, v0, v4
	v_mul_hi_u32 v0, v3, v0
	v_mul_lo_u32 v4, v0, v2
	v_sub_u32_e32 v4, v3, v4
	v_cmp_ge_u32_e32 vcc, v4, v2
	v_add_u32_e32 v5, 1, v0
	v_add_u32_e32 v3, 1, v3
	v_cndmask_b32_e32 v0, v0, v5, vcc
	v_sub_u32_e32 v5, v4, v2
	v_cndmask_b32_e32 v4, v4, v5, vcc
	v_cmp_ge_u32_e32 vcc, v4, v2
	v_add_u32_e32 v4, 1, v0
	s_nop 0
	v_cndmask_b32_e32 v0, v0, v4, vcc
	v_mul_lo_u32 v4, v2, v0
	v_add_u32_e32 v2, v4, v2
	v_cmp_ne_u32_e32 vcc, v3, v2
	v_mov_b64_e32 v[2:3], s[2:3]
	s_and_saveexec_b64 s[2:3], vcc
	s_cbranch_execz .LBB0_600
	v_readlane_b32 s4, v215, 26
	v_readlane_b32 s5, v215, 27
	s_mov_b64 s[6:7], 0
	s_nop 3
	global_load_dword v2, v1, s[4:5] sc1
	s_waitcnt vmcnt(0)
	v_cmp_eq_u32_e32 vcc, v2, v0
	s_and_saveexec_b64 s[4:5], vcc
	s_cbranch_execz .LBB0_599
	s_mov_b32 s16, 1
	s_branch .LBB0_592

.LBB0_602:
	s_or_b64 exec, exec, s[2:3]
	s_mov_b64 s[2:3], exec
	v_mbcnt_lo_u32_b32 v0, s2, 0
	v_mbcnt_hi_u32_b32 v0, s3, v0
	v_cmp_eq_u32_e32 vcc, 0, v0
	s_waitcnt vmcnt(0)
	s_and_saveexec_b64 s[4:5], vcc
	s_cbranch_execz .LBB0_604
	s_bcnt1_i32_b64 s2, s[2:3]
	v_mov_b32_e32 v0, s2
	v_readlane_b32 s2, v215, 22
	v_readlane_b32 s3, v215, 23
	s_nop 4
	global_atomic_add v1, v0, s[2:3]
